# gate1 second-half pass rewritten by hand: next-row prefetch, DPP wave reductions, no LDS
# baseline (speedup 1.0000x reference)
.LBB0_404:
	s_setprio 0
	s_cmpk_gt_i32 s26, 0x3fff
	s_barrier
	v_mbcnt_lo_u32_b32 v0, -1, 0
	v_mbcnt_hi_u32_b32 v0, -1, v0
	s_cbranch_scc1 .LBB0_407
	v_mbcnt_lo_u32_b32 v220, -1, 0
	v_mbcnt_hi_u32_b32 v220, -1, v220
	v_mov_b32_e32 v223, 0x3727c5ac
	v_lshlrev_b32_e32 v220, 4, v220
	v_add_u32_e32 v221, 0x1000, v220
	v_add_u32_e32 v222, 0x2000, v220
	s_mov_b32 s20, s26
	s_lshl_b32 s0, s20, 1
	s_and_b32 s0, s0, 0xffffe000
	s_and_b32 s1, s20, 0xfff
	s_or_b32 s0, s0, s1
	s_bitset1_b32 s0, 12
	s_mulk_i32 s0, 0x3000
	s_add_u32 s14, s62, s0
	s_addc_u32 s15, s63, 0
	s_cmpk_lt_i32 s20, 0x2000
	s_cselect_b32 s18, s60, s27
	s_cselect_b32 s19, s61, s44
	s_lshl_b32 s0, s20, 12
	s_and_b32 s0, s0, 0x1fff000
	s_add_u32 s18, s18, s0
	s_addc_u32 s19, s19, 0
	global_load_dwordx4 v[0:3], v221, s[14:15] nt
	global_load_dwordx4 v[16:19], v222, s[14:15] nt
	global_load_dwordx4 v[32:35], v220, s[18:19] nt
	global_load_dwordx4 v[4:7], v221, s[14:15] offset:1024 nt
	global_load_dwordx4 v[20:23], v222, s[14:15] offset:1024 nt
	global_load_dwordx4 v[36:39], v220, s[18:19] offset:1024 nt
	global_load_dwordx4 v[8:11], v221, s[14:15] offset:2048 nt
	global_load_dwordx4 v[24:27], v222, s[14:15] offset:2048 nt
	global_load_dwordx4 v[40:43], v220, s[18:19] offset:2048 nt
	global_load_dwordx4 v[12:15], v221, s[14:15] offset:3072 nt
	global_load_dwordx4 v[28:31], v222, s[14:15] offset:3072 nt
	global_load_dwordx4 v[44:47], v220, s[18:19] offset:3072 nt
	s_mov_b64 s[16:17], s[14:15]
	s_add_i32 s21, s20, s82
	s_cmpk_lt_i32 s21, 0x4000
	s_cbranch_scc0 .Lgate1_nopfAf
	s_lshl_b32 s0, s21, 1
	s_and_b32 s0, s0, 0xffffe000
	s_and_b32 s1, s21, 0xfff
	s_or_b32 s0, s0, s1
	s_bitset1_b32 s0, 12
	s_mulk_i32 s0, 0x3000
	s_add_u32 s14, s62, s0
	s_addc_u32 s15, s63, 0
	s_cmpk_lt_i32 s21, 0x2000
	s_cselect_b32 s18, s60, s27
	s_cselect_b32 s19, s61, s44
	s_lshl_b32 s0, s21, 12
	s_and_b32 s0, s0, 0x1fff000
	s_add_u32 s18, s18, s0
	s_addc_u32 s19, s19, 0
	global_load_dwordx4 v[48:51], v221, s[14:15] nt
	global_load_dwordx4 v[64:67], v222, s[14:15] nt
	global_load_dwordx4 v[80:83], v220, s[18:19] nt
	global_load_dwordx4 v[52:55], v221, s[14:15] offset:1024 nt
	global_load_dwordx4 v[68:71], v222, s[14:15] offset:1024 nt
	global_load_dwordx4 v[84:87], v220, s[18:19] offset:1024 nt
	global_load_dwordx4 v[56:59], v221, s[14:15] offset:2048 nt
	global_load_dwordx4 v[72:75], v222, s[14:15] offset:2048 nt
	global_load_dwordx4 v[88:91], v220, s[18:19] offset:2048 nt
	global_load_dwordx4 v[60:63], v221, s[14:15] offset:3072 nt
	global_load_dwordx4 v[76:79], v222, s[14:15] offset:3072 nt
	global_load_dwordx4 v[92:95], v220, s[18:19] offset:3072 nt
	s_waitcnt vmcnt(12)
	s_branch .Lgate1_goA
.Lgate1_nopfAf:
	s_waitcnt vmcnt(0)
	s_branch .Lgate1_goA
.Lgate1_topA:
	s_add_i32 s21, s20, s82
	s_cmpk_lt_i32 s21, 0x4000
	s_cbranch_scc0 .Lgate1_nopfA
	s_lshl_b32 s0, s21, 1
	s_and_b32 s0, s0, 0xffffe000
	s_and_b32 s1, s21, 0xfff
	s_or_b32 s0, s0, s1
	s_bitset1_b32 s0, 12
	s_mulk_i32 s0, 0x3000
	s_add_u32 s14, s62, s0
	s_addc_u32 s15, s63, 0
	s_cmpk_lt_i32 s21, 0x2000
	s_cselect_b32 s18, s60, s27
	s_cselect_b32 s19, s61, s44
	s_lshl_b32 s0, s21, 12
	s_and_b32 s0, s0, 0x1fff000
	s_add_u32 s18, s18, s0
	s_addc_u32 s19, s19, 0
	global_load_dwordx4 v[48:51], v221, s[14:15] nt
	global_load_dwordx4 v[64:67], v222, s[14:15] nt
	global_load_dwordx4 v[80:83], v220, s[18:19] nt
	global_load_dwordx4 v[52:55], v221, s[14:15] offset:1024 nt
	global_load_dwordx4 v[68:71], v222, s[14:15] offset:1024 nt
	global_load_dwordx4 v[84:87], v220, s[18:19] offset:1024 nt
	global_load_dwordx4 v[56:59], v221, s[14:15] offset:2048 nt
	global_load_dwordx4 v[72:75], v222, s[14:15] offset:2048 nt
	global_load_dwordx4 v[88:91], v220, s[18:19] offset:2048 nt
	global_load_dwordx4 v[60:63], v221, s[14:15] offset:3072 nt
	global_load_dwordx4 v[76:79], v222, s[14:15] offset:3072 nt
	global_load_dwordx4 v[92:95], v220, s[18:19] offset:3072 nt
	s_waitcnt vmcnt(16)
	s_branch .Lgate1_goA
.Lgate1_nopfA:
	s_waitcnt vmcnt(4)
.Lgate1_goA:
	v_lshlrev_b32_e32 v96, 16, v0
	v_and_b32_e32 v97, 0xffff0000, v0
	v_lshlrev_b32_e32 v160, 16, v32
	v_and_b32_e32 v161, 0xffff0000, v32
	v_lshlrev_b32_e32 v98, 16, v1
	v_and_b32_e32 v99, 0xffff0000, v1
	v_lshlrev_b32_e32 v162, 16, v33
	v_and_b32_e32 v163, 0xffff0000, v33
	v_lshlrev_b32_e32 v100, 16, v2
	v_and_b32_e32 v101, 0xffff0000, v2
	v_lshlrev_b32_e32 v164, 16, v34
	v_and_b32_e32 v165, 0xffff0000, v34
	v_lshlrev_b32_e32 v102, 16, v3
	v_and_b32_e32 v103, 0xffff0000, v3
	v_lshlrev_b32_e32 v166, 16, v35
	v_and_b32_e32 v167, 0xffff0000, v35
	v_add_f32_e32 v96, v96, v160
	v_add_f32_e32 v97, v97, v161
	v_add_f32_e32 v98, v98, v162
	v_add_f32_e32 v99, v99, v163
	v_add_f32_e32 v100, v100, v164
	v_add_f32_e32 v101, v101, v165
	v_add_f32_e32 v102, v102, v166
	v_add_f32_e32 v103, v103, v167
	v_cvt_pk_bf16_f32 v160, v96, v97
	v_cvt_pk_bf16_f32 v161, v98, v99
	v_cvt_pk_bf16_f32 v162, v100, v101
	v_cvt_pk_bf16_f32 v163, v102, v103
	v_lshlrev_b32_e32 v96, 16, v160
	v_and_b32_e32 v97, 0xffff0000, v160
	v_lshlrev_b32_e32 v98, 16, v161
	v_and_b32_e32 v99, 0xffff0000, v161
	v_lshlrev_b32_e32 v100, 16, v162
	v_and_b32_e32 v101, 0xffff0000, v162
	v_lshlrev_b32_e32 v102, 16, v163
	v_and_b32_e32 v103, 0xffff0000, v163
	v_mul_f32_e32 v192, v96, v96
	v_fmac_f32_e32 v192, v97, v97
	v_fmac_f32_e32 v192, v98, v98
	v_fmac_f32_e32 v192, v99, v99
	v_fmac_f32_e32 v192, v100, v100
	v_fmac_f32_e32 v192, v101, v101
	v_fmac_f32_e32 v192, v102, v102
	v_fmac_f32_e32 v192, v103, v103
	v_lshlrev_b32_e32 v104, 16, v4
	v_and_b32_e32 v105, 0xffff0000, v4
	v_lshlrev_b32_e32 v168, 16, v36
	v_and_b32_e32 v169, 0xffff0000, v36
	v_lshlrev_b32_e32 v106, 16, v5
	v_and_b32_e32 v107, 0xffff0000, v5
	v_lshlrev_b32_e32 v170, 16, v37
	v_and_b32_e32 v171, 0xffff0000, v37
	v_lshlrev_b32_e32 v108, 16, v6
	v_and_b32_e32 v109, 0xffff0000, v6
	v_lshlrev_b32_e32 v172, 16, v38
	v_and_b32_e32 v173, 0xffff0000, v38
	v_lshlrev_b32_e32 v110, 16, v7
	v_and_b32_e32 v111, 0xffff0000, v7
	v_lshlrev_b32_e32 v174, 16, v39
	v_and_b32_e32 v175, 0xffff0000, v39
	v_add_f32_e32 v104, v104, v168
	v_add_f32_e32 v105, v105, v169
	v_add_f32_e32 v106, v106, v170
	v_add_f32_e32 v107, v107, v171
	v_add_f32_e32 v108, v108, v172
	v_add_f32_e32 v109, v109, v173
	v_add_f32_e32 v110, v110, v174
	v_add_f32_e32 v111, v111, v175
	v_cvt_pk_bf16_f32 v168, v104, v105
	v_cvt_pk_bf16_f32 v169, v106, v107
	v_cvt_pk_bf16_f32 v170, v108, v109
	v_cvt_pk_bf16_f32 v171, v110, v111
	v_lshlrev_b32_e32 v104, 16, v168
	v_and_b32_e32 v105, 0xffff0000, v168
	v_lshlrev_b32_e32 v106, 16, v169
	v_and_b32_e32 v107, 0xffff0000, v169
	v_lshlrev_b32_e32 v108, 16, v170
	v_and_b32_e32 v109, 0xffff0000, v170
	v_lshlrev_b32_e32 v110, 16, v171
	v_and_b32_e32 v111, 0xffff0000, v171
	v_mul_f32_e32 v193, v104, v104
	v_fmac_f32_e32 v193, v105, v105
	v_fmac_f32_e32 v193, v106, v106
	v_fmac_f32_e32 v193, v107, v107
	v_fmac_f32_e32 v193, v108, v108
	v_fmac_f32_e32 v193, v109, v109
	v_fmac_f32_e32 v193, v110, v110
	v_fmac_f32_e32 v193, v111, v111
	v_lshlrev_b32_e32 v112, 16, v8
	v_and_b32_e32 v113, 0xffff0000, v8
	v_lshlrev_b32_e32 v176, 16, v40
	v_and_b32_e32 v177, 0xffff0000, v40
	v_lshlrev_b32_e32 v114, 16, v9
	v_and_b32_e32 v115, 0xffff0000, v9
	v_lshlrev_b32_e32 v178, 16, v41
	v_and_b32_e32 v179, 0xffff0000, v41
	v_lshlrev_b32_e32 v116, 16, v10
	v_and_b32_e32 v117, 0xffff0000, v10
	v_lshlrev_b32_e32 v180, 16, v42
	v_and_b32_e32 v181, 0xffff0000, v42
	v_lshlrev_b32_e32 v118, 16, v11
	v_and_b32_e32 v119, 0xffff0000, v11
	v_lshlrev_b32_e32 v182, 16, v43
	v_and_b32_e32 v183, 0xffff0000, v43
	v_add_f32_e32 v112, v112, v176
	v_add_f32_e32 v113, v113, v177
	v_add_f32_e32 v114, v114, v178
	v_add_f32_e32 v115, v115, v179
	v_add_f32_e32 v116, v116, v180
	v_add_f32_e32 v117, v117, v181
	v_add_f32_e32 v118, v118, v182
	v_add_f32_e32 v119, v119, v183
	v_cvt_pk_bf16_f32 v176, v112, v113
	v_cvt_pk_bf16_f32 v177, v114, v115
	v_cvt_pk_bf16_f32 v178, v116, v117
	v_cvt_pk_bf16_f32 v179, v118, v119
	v_lshlrev_b32_e32 v112, 16, v176
	v_and_b32_e32 v113, 0xffff0000, v176
	v_lshlrev_b32_e32 v114, 16, v177
	v_and_b32_e32 v115, 0xffff0000, v177
	v_lshlrev_b32_e32 v116, 16, v178
	v_and_b32_e32 v117, 0xffff0000, v178
	v_lshlrev_b32_e32 v118, 16, v179
	v_and_b32_e32 v119, 0xffff0000, v179
	v_mul_f32_e32 v194, v112, v112
	v_fmac_f32_e32 v194, v113, v113
	v_fmac_f32_e32 v194, v114, v114
	v_fmac_f32_e32 v194, v115, v115
	v_fmac_f32_e32 v194, v116, v116
	v_fmac_f32_e32 v194, v117, v117
	v_fmac_f32_e32 v194, v118, v118
	v_fmac_f32_e32 v194, v119, v119
	v_lshlrev_b32_e32 v120, 16, v12
	v_and_b32_e32 v121, 0xffff0000, v12
	v_lshlrev_b32_e32 v184, 16, v44
	v_and_b32_e32 v185, 0xffff0000, v44
	v_lshlrev_b32_e32 v122, 16, v13
	v_and_b32_e32 v123, 0xffff0000, v13
	v_lshlrev_b32_e32 v186, 16, v45
	v_and_b32_e32 v187, 0xffff0000, v45
	v_lshlrev_b32_e32 v124, 16, v14
	v_and_b32_e32 v125, 0xffff0000, v14
	v_lshlrev_b32_e32 v188, 16, v46
	v_and_b32_e32 v189, 0xffff0000, v46
	v_lshlrev_b32_e32 v126, 16, v15
	v_and_b32_e32 v127, 0xffff0000, v15
	v_lshlrev_b32_e32 v190, 16, v47
	v_and_b32_e32 v191, 0xffff0000, v47
	v_add_f32_e32 v120, v120, v184
	v_add_f32_e32 v121, v121, v185
	v_add_f32_e32 v122, v122, v186
	v_add_f32_e32 v123, v123, v187
	v_add_f32_e32 v124, v124, v188
	v_add_f32_e32 v125, v125, v189
	v_add_f32_e32 v126, v126, v190
	v_add_f32_e32 v127, v127, v191
	v_cvt_pk_bf16_f32 v184, v120, v121
	v_cvt_pk_bf16_f32 v185, v122, v123
	v_cvt_pk_bf16_f32 v186, v124, v125
	v_cvt_pk_bf16_f32 v187, v126, v127
	v_lshlrev_b32_e32 v120, 16, v184
	v_and_b32_e32 v121, 0xffff0000, v184
	v_lshlrev_b32_e32 v122, 16, v185
	v_and_b32_e32 v123, 0xffff0000, v185
	v_lshlrev_b32_e32 v124, 16, v186
	v_and_b32_e32 v125, 0xffff0000, v186
	v_lshlrev_b32_e32 v126, 16, v187
	v_and_b32_e32 v127, 0xffff0000, v187
	v_mul_f32_e32 v195, v120, v120
	v_fmac_f32_e32 v195, v121, v121
	v_fmac_f32_e32 v195, v122, v122
	v_fmac_f32_e32 v195, v123, v123
	v_fmac_f32_e32 v195, v124, v124
	v_fmac_f32_e32 v195, v125, v125
	v_fmac_f32_e32 v195, v126, v126
	v_fmac_f32_e32 v195, v127, v127
	s_nop 1
	v_add_f32_dpp v196, v192, v192 quad_perm:[1,0,3,2] row_mask:0xf bank_mask:0xf
	v_add_f32_dpp v197, v193, v193 quad_perm:[1,0,3,2] row_mask:0xf bank_mask:0xf
	v_add_f32_dpp v198, v194, v194 quad_perm:[1,0,3,2] row_mask:0xf bank_mask:0xf
	v_add_f32_dpp v199, v195, v195 quad_perm:[1,0,3,2] row_mask:0xf bank_mask:0xf
	v_add_f32_dpp v192, v196, v196 quad_perm:[2,3,0,1] row_mask:0xf bank_mask:0xf
	v_add_f32_dpp v193, v197, v197 quad_perm:[2,3,0,1] row_mask:0xf bank_mask:0xf
	v_add_f32_dpp v194, v198, v198 quad_perm:[2,3,0,1] row_mask:0xf bank_mask:0xf
	v_add_f32_dpp v195, v199, v199 quad_perm:[2,3,0,1] row_mask:0xf bank_mask:0xf
	v_add_f32_dpp v196, v192, v192 row_half_mirror row_mask:0xf bank_mask:0xf
	v_add_f32_dpp v197, v193, v193 row_half_mirror row_mask:0xf bank_mask:0xf
	v_add_f32_dpp v198, v194, v194 row_half_mirror row_mask:0xf bank_mask:0xf
	v_add_f32_dpp v199, v195, v195 row_half_mirror row_mask:0xf bank_mask:0xf
	v_add_f32_dpp v192, v196, v196 row_mirror row_mask:0xf bank_mask:0xf
	v_add_f32_dpp v193, v197, v197 row_mirror row_mask:0xf bank_mask:0xf
	v_add_f32_dpp v194, v198, v198 row_mirror row_mask:0xf bank_mask:0xf
	v_add_f32_dpp v195, v199, v199 row_mirror row_mask:0xf bank_mask:0xf
	s_nop 0
	v_readlane_b32 s0, v192, 0
	v_readlane_b32 s1, v192, 16
	v_readlane_b32 s6, v192, 32
	v_readlane_b32 s7, v192, 48
	s_nop 1
	v_mov_b32_e32 v196, s0
	v_add_f32_e32 v196, s1, v196
	v_add_f32_e32 v196, s6, v196
	v_add_f32_e32 v196, s7, v196
	v_fmamk_f32 v196, v196, 0x3b000000, v223
	v_readlane_b32 s0, v193, 0
	v_readlane_b32 s1, v193, 16
	v_readlane_b32 s6, v193, 32
	v_readlane_b32 s7, v193, 48
	s_nop 1
	v_mov_b32_e32 v197, s0
	v_add_f32_e32 v197, s1, v197
	v_add_f32_e32 v197, s6, v197
	v_add_f32_e32 v197, s7, v197
	v_fmamk_f32 v197, v197, 0x3b000000, v223
	v_readlane_b32 s0, v194, 0
	v_readlane_b32 s1, v194, 16
	v_readlane_b32 s6, v194, 32
	v_readlane_b32 s7, v194, 48
	s_nop 1
	v_mov_b32_e32 v198, s0
	v_add_f32_e32 v198, s1, v198
	v_add_f32_e32 v198, s6, v198
	v_add_f32_e32 v198, s7, v198
	v_fmamk_f32 v198, v198, 0x3b000000, v223
	v_readlane_b32 s0, v195, 0
	v_readlane_b32 s1, v195, 16
	v_readlane_b32 s6, v195, 32
	v_readlane_b32 s7, v195, 48
	s_nop 1
	v_mov_b32_e32 v199, s0
	v_add_f32_e32 v199, s1, v199
	v_add_f32_e32 v199, s6, v199
	v_add_f32_e32 v199, s7, v199
	v_fmamk_f32 v199, v199, 0x3b000000, v223
	v_rsq_f32_e32 v200, v196
	v_rsq_f32_e32 v201, v197
	v_rsq_f32_e32 v202, v198
	v_rsq_f32_e32 v203, v199
	v_lshlrev_b32_e32 v128, 16, v16
	v_and_b32_e32 v129, 0xffff0000, v16
	v_lshlrev_b32_e32 v130, 16, v17
	v_and_b32_e32 v131, 0xffff0000, v17
	v_lshlrev_b32_e32 v132, 16, v18
	v_and_b32_e32 v133, 0xffff0000, v18
	v_lshlrev_b32_e32 v134, 16, v19
	v_and_b32_e32 v135, 0xffff0000, v19
	v_lshlrev_b32_e32 v136, 16, v20
	v_and_b32_e32 v137, 0xffff0000, v20
	v_lshlrev_b32_e32 v138, 16, v21
	v_and_b32_e32 v139, 0xffff0000, v21
	v_lshlrev_b32_e32 v140, 16, v22
	v_and_b32_e32 v141, 0xffff0000, v22
	v_lshlrev_b32_e32 v142, 16, v23
	v_and_b32_e32 v143, 0xffff0000, v23
	v_lshlrev_b32_e32 v144, 16, v24
	v_and_b32_e32 v145, 0xffff0000, v24
	v_lshlrev_b32_e32 v146, 16, v25
	v_and_b32_e32 v147, 0xffff0000, v25
	v_lshlrev_b32_e32 v148, 16, v26
	v_and_b32_e32 v149, 0xffff0000, v26
	v_lshlrev_b32_e32 v150, 16, v27
	v_and_b32_e32 v151, 0xffff0000, v27
	v_lshlrev_b32_e32 v152, 16, v28
	v_and_b32_e32 v153, 0xffff0000, v28
	v_lshlrev_b32_e32 v154, 16, v29
	v_and_b32_e32 v155, 0xffff0000, v29
	v_lshlrev_b32_e32 v156, 16, v30
	v_and_b32_e32 v157, 0xffff0000, v30
	v_lshlrev_b32_e32 v158, 16, v31
	v_and_b32_e32 v159, 0xffff0000, v31
	v_mul_f32_e32 v160, 0xbfb8aa3b, v128
	v_mul_f32_e32 v161, 0xbfb8aa3b, v129
	v_mul_f32_e32 v162, 0xbfb8aa3b, v130
	v_mul_f32_e32 v163, 0xbfb8aa3b, v131
	v_mul_f32_e32 v164, 0xbfb8aa3b, v132
	v_mul_f32_e32 v165, 0xbfb8aa3b, v133
	v_mul_f32_e32 v166, 0xbfb8aa3b, v134
	v_mul_f32_e32 v167, 0xbfb8aa3b, v135
	v_mul_f32_e32 v168, 0xbfb8aa3b, v136
	v_mul_f32_e32 v169, 0xbfb8aa3b, v137
	v_mul_f32_e32 v170, 0xbfb8aa3b, v138
	v_mul_f32_e32 v171, 0xbfb8aa3b, v139
	v_mul_f32_e32 v172, 0xbfb8aa3b, v140
	v_mul_f32_e32 v173, 0xbfb8aa3b, v141
	v_mul_f32_e32 v174, 0xbfb8aa3b, v142
	v_mul_f32_e32 v175, 0xbfb8aa3b, v143
	v_mul_f32_e32 v176, 0xbfb8aa3b, v144
	v_mul_f32_e32 v177, 0xbfb8aa3b, v145
	v_mul_f32_e32 v178, 0xbfb8aa3b, v146
	v_mul_f32_e32 v179, 0xbfb8aa3b, v147
	v_mul_f32_e32 v180, 0xbfb8aa3b, v148
	v_mul_f32_e32 v181, 0xbfb8aa3b, v149
	v_mul_f32_e32 v182, 0xbfb8aa3b, v150
	v_mul_f32_e32 v183, 0xbfb8aa3b, v151
	v_mul_f32_e32 v184, 0xbfb8aa3b, v152
	v_mul_f32_e32 v185, 0xbfb8aa3b, v153
	v_mul_f32_e32 v186, 0xbfb8aa3b, v154
	v_mul_f32_e32 v187, 0xbfb8aa3b, v155
	v_mul_f32_e32 v188, 0xbfb8aa3b, v156
	v_mul_f32_e32 v189, 0xbfb8aa3b, v157
	v_mul_f32_e32 v190, 0xbfb8aa3b, v158
	v_mul_f32_e32 v191, 0xbfb8aa3b, v159
	v_exp_f32_e32 v160, v160
	v_exp_f32_e32 v161, v161
	v_exp_f32_e32 v162, v162
	v_exp_f32_e32 v163, v163
	v_exp_f32_e32 v164, v164
	v_exp_f32_e32 v165, v165
	v_exp_f32_e32 v166, v166
	v_exp_f32_e32 v167, v167
	v_exp_f32_e32 v168, v168
	v_exp_f32_e32 v169, v169
	v_exp_f32_e32 v170, v170
	v_exp_f32_e32 v171, v171
	v_exp_f32_e32 v172, v172
	v_exp_f32_e32 v173, v173
	v_exp_f32_e32 v174, v174
	v_exp_f32_e32 v175, v175
	v_exp_f32_e32 v176, v176
	v_exp_f32_e32 v177, v177
	v_exp_f32_e32 v178, v178
	v_exp_f32_e32 v179, v179
	v_exp_f32_e32 v180, v180
	v_exp_f32_e32 v181, v181
	v_exp_f32_e32 v182, v182
	v_exp_f32_e32 v183, v183
	v_exp_f32_e32 v184, v184
	v_exp_f32_e32 v185, v185
	v_exp_f32_e32 v186, v186
	v_exp_f32_e32 v187, v187
	v_exp_f32_e32 v188, v188
	v_exp_f32_e32 v189, v189
	v_exp_f32_e32 v190, v190
	v_exp_f32_e32 v191, v191
	v_add_f32_e32 v160, 1.0, v160
	v_add_f32_e32 v161, 1.0, v161
	v_add_f32_e32 v162, 1.0, v162
	v_add_f32_e32 v163, 1.0, v163
	v_add_f32_e32 v164, 1.0, v164
	v_add_f32_e32 v165, 1.0, v165
	v_add_f32_e32 v166, 1.0, v166
	v_add_f32_e32 v167, 1.0, v167
	v_add_f32_e32 v168, 1.0, v168
	v_add_f32_e32 v169, 1.0, v169
	v_add_f32_e32 v170, 1.0, v170
	v_add_f32_e32 v171, 1.0, v171
	v_add_f32_e32 v172, 1.0, v172
	v_add_f32_e32 v173, 1.0, v173
	v_add_f32_e32 v174, 1.0, v174
	v_add_f32_e32 v175, 1.0, v175
	v_add_f32_e32 v176, 1.0, v176
	v_add_f32_e32 v177, 1.0, v177
	v_add_f32_e32 v178, 1.0, v178
	v_add_f32_e32 v179, 1.0, v179
	v_add_f32_e32 v180, 1.0, v180
	v_add_f32_e32 v181, 1.0, v181
	v_add_f32_e32 v182, 1.0, v182
	v_add_f32_e32 v183, 1.0, v183
	v_add_f32_e32 v184, 1.0, v184
	v_add_f32_e32 v185, 1.0, v185
	v_add_f32_e32 v186, 1.0, v186
	v_add_f32_e32 v187, 1.0, v187
	v_add_f32_e32 v188, 1.0, v188
	v_add_f32_e32 v189, 1.0, v189
	v_add_f32_e32 v190, 1.0, v190
	v_add_f32_e32 v191, 1.0, v191
	v_rcp_f32_e32 v160, v160
	v_rcp_f32_e32 v161, v161
	v_rcp_f32_e32 v162, v162
	v_rcp_f32_e32 v163, v163
	v_rcp_f32_e32 v164, v164
	v_rcp_f32_e32 v165, v165
	v_rcp_f32_e32 v166, v166
	v_rcp_f32_e32 v167, v167
	v_rcp_f32_e32 v168, v168
	v_rcp_f32_e32 v169, v169
	v_rcp_f32_e32 v170, v170
	v_rcp_f32_e32 v171, v171
	v_rcp_f32_e32 v172, v172
	v_rcp_f32_e32 v173, v173
	v_rcp_f32_e32 v174, v174
	v_rcp_f32_e32 v175, v175
	v_rcp_f32_e32 v176, v176
	v_rcp_f32_e32 v177, v177
	v_rcp_f32_e32 v178, v178
	v_rcp_f32_e32 v179, v179
	v_rcp_f32_e32 v180, v180
	v_rcp_f32_e32 v181, v181
	v_rcp_f32_e32 v182, v182
	v_rcp_f32_e32 v183, v183
	v_rcp_f32_e32 v184, v184
	v_rcp_f32_e32 v185, v185
	v_rcp_f32_e32 v186, v186
	v_rcp_f32_e32 v187, v187
	v_rcp_f32_e32 v188, v188
	v_rcp_f32_e32 v189, v189
	v_rcp_f32_e32 v190, v190
	v_rcp_f32_e32 v191, v191
	v_mul_f32_e32 v128, v160, v128
	v_mul_f32_e32 v129, v161, v129
	v_mul_f32_e32 v130, v162, v130
	v_mul_f32_e32 v131, v163, v131
	v_mul_f32_e32 v132, v164, v132
	v_mul_f32_e32 v133, v165, v133
	v_mul_f32_e32 v134, v166, v134
	v_mul_f32_e32 v135, v167, v135
	v_mul_f32_e32 v136, v168, v136
	v_mul_f32_e32 v137, v169, v137
	v_mul_f32_e32 v138, v170, v138
	v_mul_f32_e32 v139, v171, v139
	v_mul_f32_e32 v140, v172, v140
	v_mul_f32_e32 v141, v173, v141
	v_mul_f32_e32 v142, v174, v142
	v_mul_f32_e32 v143, v175, v143
	v_mul_f32_e32 v144, v176, v144
	v_mul_f32_e32 v145, v177, v145
	v_mul_f32_e32 v146, v178, v146
	v_mul_f32_e32 v147, v179, v147
	v_mul_f32_e32 v148, v180, v148
	v_mul_f32_e32 v149, v181, v149
	v_mul_f32_e32 v150, v182, v150
	v_mul_f32_e32 v151, v183, v151
	v_mul_f32_e32 v152, v184, v152
	v_mul_f32_e32 v153, v185, v153
	v_mul_f32_e32 v154, v186, v154
	v_mul_f32_e32 v155, v187, v155
	v_mul_f32_e32 v156, v188, v156
	v_mul_f32_e32 v157, v189, v157
	v_mul_f32_e32 v158, v190, v158
	v_mul_f32_e32 v159, v191, v159
	v_mul_f32_e32 v128, v128, v96
	v_mul_f32_e32 v129, v129, v97
	v_mul_f32_e32 v130, v130, v98
	v_mul_f32_e32 v131, v131, v99
	v_mul_f32_e32 v132, v132, v100
	v_mul_f32_e32 v133, v133, v101
	v_mul_f32_e32 v134, v134, v102
	v_mul_f32_e32 v135, v135, v103
	v_mul_f32_e32 v136, v136, v104
	v_mul_f32_e32 v137, v137, v105
	v_mul_f32_e32 v138, v138, v106
	v_mul_f32_e32 v139, v139, v107
	v_mul_f32_e32 v140, v140, v108
	v_mul_f32_e32 v141, v141, v109
	v_mul_f32_e32 v142, v142, v110
	v_mul_f32_e32 v143, v143, v111
	v_mul_f32_e32 v144, v144, v112
	v_mul_f32_e32 v145, v145, v113
	v_mul_f32_e32 v146, v146, v114
	v_mul_f32_e32 v147, v147, v115
	v_mul_f32_e32 v148, v148, v116
	v_mul_f32_e32 v149, v149, v117
	v_mul_f32_e32 v150, v150, v118
	v_mul_f32_e32 v151, v151, v119
	v_mul_f32_e32 v152, v152, v120
	v_mul_f32_e32 v153, v153, v121
	v_mul_f32_e32 v154, v154, v122
	v_mul_f32_e32 v155, v155, v123
	v_mul_f32_e32 v156, v156, v124
	v_mul_f32_e32 v157, v157, v125
	v_mul_f32_e32 v158, v158, v126
	v_mul_f32_e32 v159, v159, v127
	v_mul_f32_e32 v128, v128, v200
	v_mul_f32_e32 v129, v129, v200
	v_mul_f32_e32 v130, v130, v200
	v_mul_f32_e32 v131, v131, v200
	v_mul_f32_e32 v132, v132, v200
	v_mul_f32_e32 v133, v133, v200
	v_mul_f32_e32 v134, v134, v200
	v_mul_f32_e32 v135, v135, v200
	v_mul_f32_e32 v136, v136, v201
	v_mul_f32_e32 v137, v137, v201
	v_mul_f32_e32 v138, v138, v201
	v_mul_f32_e32 v139, v139, v201
	v_mul_f32_e32 v140, v140, v201
	v_mul_f32_e32 v141, v141, v201
	v_mul_f32_e32 v142, v142, v201
	v_mul_f32_e32 v143, v143, v201
	v_mul_f32_e32 v144, v144, v202
	v_mul_f32_e32 v145, v145, v202
	v_mul_f32_e32 v146, v146, v202
	v_mul_f32_e32 v147, v147, v202
	v_mul_f32_e32 v148, v148, v202
	v_mul_f32_e32 v149, v149, v202
	v_mul_f32_e32 v150, v150, v202
	v_mul_f32_e32 v151, v151, v202
	v_mul_f32_e32 v152, v152, v203
	v_mul_f32_e32 v153, v153, v203
	v_mul_f32_e32 v154, v154, v203
	v_mul_f32_e32 v155, v155, v203
	v_mul_f32_e32 v156, v156, v203
	v_mul_f32_e32 v157, v157, v203
	v_mul_f32_e32 v158, v158, v203
	v_mul_f32_e32 v159, v159, v203
	v_cvt_pk_bf16_f32 v204, v128, v129
	v_cvt_pk_bf16_f32 v205, v130, v131
	v_cvt_pk_bf16_f32 v206, v132, v133
	v_cvt_pk_bf16_f32 v207, v134, v135
	v_cvt_pk_bf16_f32 v208, v136, v137
	v_cvt_pk_bf16_f32 v209, v138, v139
	v_cvt_pk_bf16_f32 v210, v140, v141
	v_cvt_pk_bf16_f32 v211, v142, v143
	v_cvt_pk_bf16_f32 v212, v144, v145
	v_cvt_pk_bf16_f32 v213, v146, v147
	v_cvt_pk_bf16_f32 v214, v148, v149
	v_cvt_pk_bf16_f32 v215, v150, v151
	v_cvt_pk_bf16_f32 v216, v152, v153
	v_cvt_pk_bf16_f32 v217, v154, v155
	v_cvt_pk_bf16_f32 v218, v156, v157
	v_cvt_pk_bf16_f32 v219, v158, v159
	global_store_dwordx4 v222, v[204:207], s[16:17] nt
	global_store_dwordx4 v222, v[208:211], s[16:17] offset:1024 nt
	global_store_dwordx4 v222, v[212:215], s[16:17] offset:2048 nt
	global_store_dwordx4 v222, v[216:219], s[16:17] offset:3072 nt
	s_cmpk_lt_i32 s21, 0x4000
	s_cbranch_scc0 .Lgate1_done
	s_mov_b32 s20, s21
	s_mov_b64 s[16:17], s[14:15]
	s_add_i32 s21, s20, s82
	s_cmpk_lt_i32 s21, 0x4000
	s_cbranch_scc0 .Lgate1_nopfB
	s_lshl_b32 s0, s21, 1
	s_and_b32 s0, s0, 0xffffe000
	s_and_b32 s1, s21, 0xfff
	s_or_b32 s0, s0, s1
	s_bitset1_b32 s0, 12
	s_mulk_i32 s0, 0x3000
	s_add_u32 s14, s62, s0
	s_addc_u32 s15, s63, 0
	s_cmpk_lt_i32 s21, 0x2000
	s_cselect_b32 s18, s60, s27
	s_cselect_b32 s19, s61, s44
	s_lshl_b32 s0, s21, 12
	s_and_b32 s0, s0, 0x1fff000
	s_add_u32 s18, s18, s0
	s_addc_u32 s19, s19, 0
	global_load_dwordx4 v[0:3], v221, s[14:15] nt
	global_load_dwordx4 v[16:19], v222, s[14:15] nt
	global_load_dwordx4 v[32:35], v220, s[18:19] nt
	global_load_dwordx4 v[4:7], v221, s[14:15] offset:1024 nt
	global_load_dwordx4 v[20:23], v222, s[14:15] offset:1024 nt
	global_load_dwordx4 v[36:39], v220, s[18:19] offset:1024 nt
	global_load_dwordx4 v[8:11], v221, s[14:15] offset:2048 nt
	global_load_dwordx4 v[24:27], v222, s[14:15] offset:2048 nt
	global_load_dwordx4 v[40:43], v220, s[18:19] offset:2048 nt
	global_load_dwordx4 v[12:15], v221, s[14:15] offset:3072 nt
	global_load_dwordx4 v[28:31], v222, s[14:15] offset:3072 nt
	global_load_dwordx4 v[44:47], v220, s[18:19] offset:3072 nt
	s_waitcnt vmcnt(16)
	s_branch .Lgate1_goB

.Lgate1_goB:
	v_lshlrev_b32_e32 v96, 16, v48
	v_and_b32_e32 v97, 0xffff0000, v48
	v_lshlrev_b32_e32 v160, 16, v80
	v_and_b32_e32 v161, 0xffff0000, v80
	v_lshlrev_b32_e32 v98, 16, v49
	v_and_b32_e32 v99, 0xffff0000, v49
	v_lshlrev_b32_e32 v162, 16, v81
	v_and_b32_e32 v163, 0xffff0000, v81
	v_lshlrev_b32_e32 v100, 16, v50
	v_and_b32_e32 v101, 0xffff0000, v50
	v_lshlrev_b32_e32 v164, 16, v82
	v_and_b32_e32 v165, 0xffff0000, v82
	v_lshlrev_b32_e32 v102, 16, v51
	v_and_b32_e32 v103, 0xffff0000, v51
	v_lshlrev_b32_e32 v166, 16, v83
	v_and_b32_e32 v167, 0xffff0000, v83
	v_add_f32_e32 v96, v96, v160
	v_add_f32_e32 v97, v97, v161
	v_add_f32_e32 v98, v98, v162
	v_add_f32_e32 v99, v99, v163
	v_add_f32_e32 v100, v100, v164
	v_add_f32_e32 v101, v101, v165
	v_add_f32_e32 v102, v102, v166
	v_add_f32_e32 v103, v103, v167
	v_cvt_pk_bf16_f32 v160, v96, v97
	v_cvt_pk_bf16_f32 v161, v98, v99
	v_cvt_pk_bf16_f32 v162, v100, v101
	v_cvt_pk_bf16_f32 v163, v102, v103
	v_lshlrev_b32_e32 v96, 16, v160
	v_and_b32_e32 v97, 0xffff0000, v160
	v_lshlrev_b32_e32 v98, 16, v161
	v_and_b32_e32 v99, 0xffff0000, v161
	v_lshlrev_b32_e32 v100, 16, v162
	v_and_b32_e32 v101, 0xffff0000, v162
	v_lshlrev_b32_e32 v102, 16, v163
	v_and_b32_e32 v103, 0xffff0000, v163
	v_mul_f32_e32 v192, v96, v96
	v_fmac_f32_e32 v192, v97, v97
	v_fmac_f32_e32 v192, v98, v98
	v_fmac_f32_e32 v192, v99, v99
	v_fmac_f32_e32 v192, v100, v100
	v_fmac_f32_e32 v192, v101, v101
	v_fmac_f32_e32 v192, v102, v102
	v_fmac_f32_e32 v192, v103, v103
	v_lshlrev_b32_e32 v104, 16, v52
	v_and_b32_e32 v105, 0xffff0000, v52
	v_lshlrev_b32_e32 v168, 16, v84
	v_and_b32_e32 v169, 0xffff0000, v84
	v_lshlrev_b32_e32 v106, 16, v53
	v_and_b32_e32 v107, 0xffff0000, v53
	v_lshlrev_b32_e32 v170, 16, v85
	v_and_b32_e32 v171, 0xffff0000, v85
	v_lshlrev_b32_e32 v108, 16, v54
	v_and_b32_e32 v109, 0xffff0000, v54
	v_lshlrev_b32_e32 v172, 16, v86
	v_and_b32_e32 v173, 0xffff0000, v86
	v_lshlrev_b32_e32 v110, 16, v55
	v_and_b32_e32 v111, 0xffff0000, v55
	v_lshlrev_b32_e32 v174, 16, v87
	v_and_b32_e32 v175, 0xffff0000, v87
	v_add_f32_e32 v104, v104, v168
	v_add_f32_e32 v105, v105, v169
	v_add_f32_e32 v106, v106, v170
	v_add_f32_e32 v107, v107, v171
	v_add_f32_e32 v108, v108, v172
	v_add_f32_e32 v109, v109, v173
	v_add_f32_e32 v110, v110, v174
	v_add_f32_e32 v111, v111, v175
	v_cvt_pk_bf16_f32 v168, v104, v105
	v_cvt_pk_bf16_f32 v169, v106, v107
	v_cvt_pk_bf16_f32 v170, v108, v109
	v_cvt_pk_bf16_f32 v171, v110, v111
	v_lshlrev_b32_e32 v104, 16, v168
	v_and_b32_e32 v105, 0xffff0000, v168
	v_lshlrev_b32_e32 v106, 16, v169
	v_and_b32_e32 v107, 0xffff0000, v169
	v_lshlrev_b32_e32 v108, 16, v170
	v_and_b32_e32 v109, 0xffff0000, v170
	v_lshlrev_b32_e32 v110, 16, v171
	v_and_b32_e32 v111, 0xffff0000, v171
	v_mul_f32_e32 v193, v104, v104
	v_fmac_f32_e32 v193, v105, v105
	v_fmac_f32_e32 v193, v106, v106
	v_fmac_f32_e32 v193, v107, v107
	v_fmac_f32_e32 v193, v108, v108
	v_fmac_f32_e32 v193, v109, v109
	v_fmac_f32_e32 v193, v110, v110
	v_fmac_f32_e32 v193, v111, v111
	v_lshlrev_b32_e32 v112, 16, v56
	v_and_b32_e32 v113, 0xffff0000, v56
	v_lshlrev_b32_e32 v176, 16, v88
	v_and_b32_e32 v177, 0xffff0000, v88
	v_lshlrev_b32_e32 v114, 16, v57
	v_and_b32_e32 v115, 0xffff0000, v57
	v_lshlrev_b32_e32 v178, 16, v89
	v_and_b32_e32 v179, 0xffff0000, v89
	v_lshlrev_b32_e32 v116, 16, v58
	v_and_b32_e32 v117, 0xffff0000, v58
	v_lshlrev_b32_e32 v180, 16, v90
	v_and_b32_e32 v181, 0xffff0000, v90
	v_lshlrev_b32_e32 v118, 16, v59
	v_and_b32_e32 v119, 0xffff0000, v59
	v_lshlrev_b32_e32 v182, 16, v91
	v_and_b32_e32 v183, 0xffff0000, v91
	v_add_f32_e32 v112, v112, v176
	v_add_f32_e32 v113, v113, v177
	v_add_f32_e32 v114, v114, v178
	v_add_f32_e32 v115, v115, v179
	v_add_f32_e32 v116, v116, v180
	v_add_f32_e32 v117, v117, v181
	v_add_f32_e32 v118, v118, v182
	v_add_f32_e32 v119, v119, v183
	v_cvt_pk_bf16_f32 v176, v112, v113
	v_cvt_pk_bf16_f32 v177, v114, v115
	v_cvt_pk_bf16_f32 v178, v116, v117
	v_cvt_pk_bf16_f32 v179, v118, v119
	v_lshlrev_b32_e32 v112, 16, v176
	v_and_b32_e32 v113, 0xffff0000, v176
	v_lshlrev_b32_e32 v114, 16, v177
	v_and_b32_e32 v115, 0xffff0000, v177
	v_lshlrev_b32_e32 v116, 16, v178
	v_and_b32_e32 v117, 0xffff0000, v178
	v_lshlrev_b32_e32 v118, 16, v179
	v_and_b32_e32 v119, 0xffff0000, v179
	v_mul_f32_e32 v194, v112, v112
	v_fmac_f32_e32 v194, v113, v113
	v_fmac_f32_e32 v194, v114, v114
	v_fmac_f32_e32 v194, v115, v115
	v_fmac_f32_e32 v194, v116, v116
	v_fmac_f32_e32 v194, v117, v117
	v_fmac_f32_e32 v194, v118, v118
	v_fmac_f32_e32 v194, v119, v119
	v_lshlrev_b32_e32 v120, 16, v60
	v_and_b32_e32 v121, 0xffff0000, v60
	v_lshlrev_b32_e32 v184, 16, v92
	v_and_b32_e32 v185, 0xffff0000, v92
	v_lshlrev_b32_e32 v122, 16, v61
	v_and_b32_e32 v123, 0xffff0000, v61
	v_lshlrev_b32_e32 v186, 16, v93
	v_and_b32_e32 v187, 0xffff0000, v93
	v_lshlrev_b32_e32 v124, 16, v62
	v_and_b32_e32 v125, 0xffff0000, v62
	v_lshlrev_b32_e32 v188, 16, v94
	v_and_b32_e32 v189, 0xffff0000, v94
	v_lshlrev_b32_e32 v126, 16, v63
	v_and_b32_e32 v127, 0xffff0000, v63
	v_lshlrev_b32_e32 v190, 16, v95
	v_and_b32_e32 v191, 0xffff0000, v95
	v_add_f32_e32 v120, v120, v184
	v_add_f32_e32 v121, v121, v185
	v_add_f32_e32 v122, v122, v186
	v_add_f32_e32 v123, v123, v187
	v_add_f32_e32 v124, v124, v188
	v_add_f32_e32 v125, v125, v189
	v_add_f32_e32 v126, v126, v190
	v_add_f32_e32 v127, v127, v191
	v_cvt_pk_bf16_f32 v184, v120, v121
	v_cvt_pk_bf16_f32 v185, v122, v123
	v_cvt_pk_bf16_f32 v186, v124, v125
	v_cvt_pk_bf16_f32 v187, v126, v127
	v_lshlrev_b32_e32 v120, 16, v184
	v_and_b32_e32 v121, 0xffff0000, v184
	v_lshlrev_b32_e32 v122, 16, v185
	v_and_b32_e32 v123, 0xffff0000, v185
	v_lshlrev_b32_e32 v124, 16, v186
	v_and_b32_e32 v125, 0xffff0000, v186
	v_lshlrev_b32_e32 v126, 16, v187
	v_and_b32_e32 v127, 0xffff0000, v187
	v_mul_f32_e32 v195, v120, v120
	v_fmac_f32_e32 v195, v121, v121
	v_fmac_f32_e32 v195, v122, v122
	v_fmac_f32_e32 v195, v123, v123
	v_fmac_f32_e32 v195, v124, v124
	v_fmac_f32_e32 v195, v125, v125
	v_fmac_f32_e32 v195, v126, v126
	v_fmac_f32_e32 v195, v127, v127
	s_nop 1
	v_add_f32_dpp v196, v192, v192 quad_perm:[1,0,3,2] row_mask:0xf bank_mask:0xf
	v_add_f32_dpp v197, v193, v193 quad_perm:[1,0,3,2] row_mask:0xf bank_mask:0xf
	v_add_f32_dpp v198, v194, v194 quad_perm:[1,0,3,2] row_mask:0xf bank_mask:0xf
	v_add_f32_dpp v199, v195, v195 quad_perm:[1,0,3,2] row_mask:0xf bank_mask:0xf
	v_add_f32_dpp v192, v196, v196 quad_perm:[2,3,0,1] row_mask:0xf bank_mask:0xf
	v_add_f32_dpp v193, v197, v197 quad_perm:[2,3,0,1] row_mask:0xf bank_mask:0xf
	v_add_f32_dpp v194, v198, v198 quad_perm:[2,3,0,1] row_mask:0xf bank_mask:0xf
	v_add_f32_dpp v195, v199, v199 quad_perm:[2,3,0,1] row_mask:0xf bank_mask:0xf
	v_add_f32_dpp v196, v192, v192 row_half_mirror row_mask:0xf bank_mask:0xf
	v_add_f32_dpp v197, v193, v193 row_half_mirror row_mask:0xf bank_mask:0xf
	v_add_f32_dpp v198, v194, v194 row_half_mirror row_mask:0xf bank_mask:0xf
	v_add_f32_dpp v199, v195, v195 row_half_mirror row_mask:0xf bank_mask:0xf
	v_add_f32_dpp v192, v196, v196 row_mirror row_mask:0xf bank_mask:0xf
	v_add_f32_dpp v193, v197, v197 row_mirror row_mask:0xf bank_mask:0xf
	v_add_f32_dpp v194, v198, v198 row_mirror row_mask:0xf bank_mask:0xf
	v_add_f32_dpp v195, v199, v199 row_mirror row_mask:0xf bank_mask:0xf
	s_nop 0
	v_readlane_b32 s0, v192, 0
	v_readlane_b32 s1, v192, 16
	v_readlane_b32 s6, v192, 32
	v_readlane_b32 s7, v192, 48
	s_nop 1
	v_mov_b32_e32 v196, s0
	v_add_f32_e32 v196, s1, v196
	v_add_f32_e32 v196, s6, v196
	v_add_f32_e32 v196, s7, v196
	v_fmamk_f32 v196, v196, 0x3b000000, v223
	v_readlane_b32 s0, v193, 0
	v_readlane_b32 s1, v193, 16
	v_readlane_b32 s6, v193, 32
	v_readlane_b32 s7, v193, 48
	s_nop 1
	v_mov_b32_e32 v197, s0
	v_add_f32_e32 v197, s1, v197
	v_add_f32_e32 v197, s6, v197
	v_add_f32_e32 v197, s7, v197
	v_fmamk_f32 v197, v197, 0x3b000000, v223
	v_readlane_b32 s0, v194, 0
	v_readlane_b32 s1, v194, 16
	v_readlane_b32 s6, v194, 32
	v_readlane_b32 s7, v194, 48
	s_nop 1
	v_mov_b32_e32 v198, s0
	v_add_f32_e32 v198, s1, v198
	v_add_f32_e32 v198, s6, v198
	v_add_f32_e32 v198, s7, v198
	v_fmamk_f32 v198, v198, 0x3b000000, v223
	v_readlane_b32 s0, v195, 0
	v_readlane_b32 s1, v195, 16
	v_readlane_b32 s6, v195, 32
	v_readlane_b32 s7, v195, 48
	s_nop 1
	v_mov_b32_e32 v199, s0
	v_add_f32_e32 v199, s1, v199
	v_add_f32_e32 v199, s6, v199
	v_add_f32_e32 v199, s7, v199
	v_fmamk_f32 v199, v199, 0x3b000000, v223
	v_rsq_f32_e32 v200, v196
	v_rsq_f32_e32 v201, v197
	v_rsq_f32_e32 v202, v198
	v_rsq_f32_e32 v203, v199
	v_lshlrev_b32_e32 v128, 16, v64
	v_and_b32_e32 v129, 0xffff0000, v64
	v_lshlrev_b32_e32 v130, 16, v65
	v_and_b32_e32 v131, 0xffff0000, v65
	v_lshlrev_b32_e32 v132, 16, v66
	v_and_b32_e32 v133, 0xffff0000, v66
	v_lshlrev_b32_e32 v134, 16, v67
	v_and_b32_e32 v135, 0xffff0000, v67
	v_lshlrev_b32_e32 v136, 16, v68
	v_and_b32_e32 v137, 0xffff0000, v68
	v_lshlrev_b32_e32 v138, 16, v69
	v_and_b32_e32 v139, 0xffff0000, v69
	v_lshlrev_b32_e32 v140, 16, v70
	v_and_b32_e32 v141, 0xffff0000, v70
	v_lshlrev_b32_e32 v142, 16, v71
	v_and_b32_e32 v143, 0xffff0000, v71
	v_lshlrev_b32_e32 v144, 16, v72
	v_and_b32_e32 v145, 0xffff0000, v72
	v_lshlrev_b32_e32 v146, 16, v73
	v_and_b32_e32 v147, 0xffff0000, v73
	v_lshlrev_b32_e32 v148, 16, v74
	v_and_b32_e32 v149, 0xffff0000, v74
	v_lshlrev_b32_e32 v150, 16, v75
	v_and_b32_e32 v151, 0xffff0000, v75
	v_lshlrev_b32_e32 v152, 16, v76
	v_and_b32_e32 v153, 0xffff0000, v76
	v_lshlrev_b32_e32 v154, 16, v77
	v_and_b32_e32 v155, 0xffff0000, v77
	v_lshlrev_b32_e32 v156, 16, v78
	v_and_b32_e32 v157, 0xffff0000, v78
	v_lshlrev_b32_e32 v158, 16, v79
	v_and_b32_e32 v159, 0xffff0000, v79
	v_mul_f32_e32 v160, 0xbfb8aa3b, v128
	v_mul_f32_e32 v161, 0xbfb8aa3b, v129
	v_mul_f32_e32 v162, 0xbfb8aa3b, v130
	v_mul_f32_e32 v163, 0xbfb8aa3b, v131
	v_mul_f32_e32 v164, 0xbfb8aa3b, v132
	v_mul_f32_e32 v165, 0xbfb8aa3b, v133
	v_mul_f32_e32 v166, 0xbfb8aa3b, v134
	v_mul_f32_e32 v167, 0xbfb8aa3b, v135
	v_mul_f32_e32 v168, 0xbfb8aa3b, v136
	v_mul_f32_e32 v169, 0xbfb8aa3b, v137
	v_mul_f32_e32 v170, 0xbfb8aa3b, v138
	v_mul_f32_e32 v171, 0xbfb8aa3b, v139
	v_mul_f32_e32 v172, 0xbfb8aa3b, v140
	v_mul_f32_e32 v173, 0xbfb8aa3b, v141
	v_mul_f32_e32 v174, 0xbfb8aa3b, v142
	v_mul_f32_e32 v175, 0xbfb8aa3b, v143
	v_mul_f32_e32 v176, 0xbfb8aa3b, v144
	v_mul_f32_e32 v177, 0xbfb8aa3b, v145
	v_mul_f32_e32 v178, 0xbfb8aa3b, v146
	v_mul_f32_e32 v179, 0xbfb8aa3b, v147
	v_mul_f32_e32 v180, 0xbfb8aa3b, v148
	v_mul_f32_e32 v181, 0xbfb8aa3b, v149
	v_mul_f32_e32 v182, 0xbfb8aa3b, v150
	v_mul_f32_e32 v183, 0xbfb8aa3b, v151
	v_mul_f32_e32 v184, 0xbfb8aa3b, v152
	v_mul_f32_e32 v185, 0xbfb8aa3b, v153
	v_mul_f32_e32 v186, 0xbfb8aa3b, v154
	v_mul_f32_e32 v187, 0xbfb8aa3b, v155
	v_mul_f32_e32 v188, 0xbfb8aa3b, v156
	v_mul_f32_e32 v189, 0xbfb8aa3b, v157
	v_mul_f32_e32 v190, 0xbfb8aa3b, v158
	v_mul_f32_e32 v191, 0xbfb8aa3b, v159
	v_exp_f32_e32 v160, v160
	v_exp_f32_e32 v161, v161
	v_exp_f32_e32 v162, v162
	v_exp_f32_e32 v163, v163
	v_exp_f32_e32 v164, v164
	v_exp_f32_e32 v165, v165
	v_exp_f32_e32 v166, v166
	v_exp_f32_e32 v167, v167
	v_exp_f32_e32 v168, v168
	v_exp_f32_e32 v169, v169
	v_exp_f32_e32 v170, v170
	v_exp_f32_e32 v171, v171
	v_exp_f32_e32 v172, v172
	v_exp_f32_e32 v173, v173
	v_exp_f32_e32 v174, v174
	v_exp_f32_e32 v175, v175
	v_exp_f32_e32 v176, v176
	v_exp_f32_e32 v177, v177
	v_exp_f32_e32 v178, v178
	v_exp_f32_e32 v179, v179
	v_exp_f32_e32 v180, v180
	v_exp_f32_e32 v181, v181
	v_exp_f32_e32 v182, v182
	v_exp_f32_e32 v183, v183
	v_exp_f32_e32 v184, v184
	v_exp_f32_e32 v185, v185
	v_exp_f32_e32 v186, v186
	v_exp_f32_e32 v187, v187
	v_exp_f32_e32 v188, v188
	v_exp_f32_e32 v189, v189
	v_exp_f32_e32 v190, v190
	v_exp_f32_e32 v191, v191
	v_add_f32_e32 v160, 1.0, v160
	v_add_f32_e32 v161, 1.0, v161
	v_add_f32_e32 v162, 1.0, v162
	v_add_f32_e32 v163, 1.0, v163
	v_add_f32_e32 v164, 1.0, v164
	v_add_f32_e32 v165, 1.0, v165
	v_add_f32_e32 v166, 1.0, v166
	v_add_f32_e32 v167, 1.0, v167
	v_add_f32_e32 v168, 1.0, v168
	v_add_f32_e32 v169, 1.0, v169
	v_add_f32_e32 v170, 1.0, v170
	v_add_f32_e32 v171, 1.0, v171
	v_add_f32_e32 v172, 1.0, v172
	v_add_f32_e32 v173, 1.0, v173
	v_add_f32_e32 v174, 1.0, v174
	v_add_f32_e32 v175, 1.0, v175
	v_add_f32_e32 v176, 1.0, v176
	v_add_f32_e32 v177, 1.0, v177
	v_add_f32_e32 v178, 1.0, v178
	v_add_f32_e32 v179, 1.0, v179
	v_add_f32_e32 v180, 1.0, v180
	v_add_f32_e32 v181, 1.0, v181
	v_add_f32_e32 v182, 1.0, v182
	v_add_f32_e32 v183, 1.0, v183
	v_add_f32_e32 v184, 1.0, v184
	v_add_f32_e32 v185, 1.0, v185
	v_add_f32_e32 v186, 1.0, v186
	v_add_f32_e32 v187, 1.0, v187
	v_add_f32_e32 v188, 1.0, v188
	v_add_f32_e32 v189, 1.0, v189
	v_add_f32_e32 v190, 1.0, v190
	v_add_f32_e32 v191, 1.0, v191
	v_rcp_f32_e32 v160, v160
	v_rcp_f32_e32 v161, v161
	v_rcp_f32_e32 v162, v162
	v_rcp_f32_e32 v163, v163
	v_rcp_f32_e32 v164, v164
	v_rcp_f32_e32 v165, v165
	v_rcp_f32_e32 v166, v166
	v_rcp_f32_e32 v167, v167
	v_rcp_f32_e32 v168, v168
	v_rcp_f32_e32 v169, v169
	v_rcp_f32_e32 v170, v170
	v_rcp_f32_e32 v171, v171
	v_rcp_f32_e32 v172, v172
	v_rcp_f32_e32 v173, v173
	v_rcp_f32_e32 v174, v174
	v_rcp_f32_e32 v175, v175
	v_rcp_f32_e32 v176, v176
	v_rcp_f32_e32 v177, v177
	v_rcp_f32_e32 v178, v178
	v_rcp_f32_e32 v179, v179
	v_rcp_f32_e32 v180, v180
	v_rcp_f32_e32 v181, v181
	v_rcp_f32_e32 v182, v182
	v_rcp_f32_e32 v183, v183
	v_rcp_f32_e32 v184, v184
	v_rcp_f32_e32 v185, v185
	v_rcp_f32_e32 v186, v186
	v_rcp_f32_e32 v187, v187
	v_rcp_f32_e32 v188, v188
	v_rcp_f32_e32 v189, v189
	v_rcp_f32_e32 v190, v190
	v_rcp_f32_e32 v191, v191
	v_mul_f32_e32 v128, v160, v128
	v_mul_f32_e32 v129, v161, v129
	v_mul_f32_e32 v130, v162, v130
	v_mul_f32_e32 v131, v163, v131
	v_mul_f32_e32 v132, v164, v132
	v_mul_f32_e32 v133, v165, v133
	v_mul_f32_e32 v134, v166, v134
	v_mul_f32_e32 v135, v167, v135
	v_mul_f32_e32 v136, v168, v136
	v_mul_f32_e32 v137, v169, v137
	v_mul_f32_e32 v138, v170, v138
	v_mul_f32_e32 v139, v171, v139
	v_mul_f32_e32 v140, v172, v140
	v_mul_f32_e32 v141, v173, v141
	v_mul_f32_e32 v142, v174, v142
	v_mul_f32_e32 v143, v175, v143
	v_mul_f32_e32 v144, v176, v144
	v_mul_f32_e32 v145, v177, v145
	v_mul_f32_e32 v146, v178, v146
	v_mul_f32_e32 v147, v179, v147
	v_mul_f32_e32 v148, v180, v148
	v_mul_f32_e32 v149, v181, v149
	v_mul_f32_e32 v150, v182, v150
	v_mul_f32_e32 v151, v183, v151
	v_mul_f32_e32 v152, v184, v152
	v_mul_f32_e32 v153, v185, v153
	v_mul_f32_e32 v154, v186, v154
	v_mul_f32_e32 v155, v187, v155
	v_mul_f32_e32 v156, v188, v156
	v_mul_f32_e32 v157, v189, v157
	v_mul_f32_e32 v158, v190, v158
	v_mul_f32_e32 v159, v191, v159
	v_mul_f32_e32 v128, v128, v96
	v_mul_f32_e32 v129, v129, v97
	v_mul_f32_e32 v130, v130, v98
	v_mul_f32_e32 v131, v131, v99
	v_mul_f32_e32 v132, v132, v100
	v_mul_f32_e32 v133, v133, v101
	v_mul_f32_e32 v134, v134, v102
	v_mul_f32_e32 v135, v135, v103
	v_mul_f32_e32 v136, v136, v104
	v_mul_f32_e32 v137, v137, v105
	v_mul_f32_e32 v138, v138, v106
	v_mul_f32_e32 v139, v139, v107
	v_mul_f32_e32 v140, v140, v108
	v_mul_f32_e32 v141, v141, v109
	v_mul_f32_e32 v142, v142, v110
	v_mul_f32_e32 v143, v143, v111
	v_mul_f32_e32 v144, v144, v112
	v_mul_f32_e32 v145, v145, v113
	v_mul_f32_e32 v146, v146, v114
	v_mul_f32_e32 v147, v147, v115
	v_mul_f32_e32 v148, v148, v116
	v_mul_f32_e32 v149, v149, v117
	v_mul_f32_e32 v150, v150, v118
	v_mul_f32_e32 v151, v151, v119
	v_mul_f32_e32 v152, v152, v120
	v_mul_f32_e32 v153, v153, v121
	v_mul_f32_e32 v154, v154, v122
	v_mul_f32_e32 v155, v155, v123
	v_mul_f32_e32 v156, v156, v124
	v_mul_f32_e32 v157, v157, v125
	v_mul_f32_e32 v158, v158, v126
	v_mul_f32_e32 v159, v159, v127
	v_mul_f32_e32 v128, v128, v200
	v_mul_f32_e32 v129, v129, v200
	v_mul_f32_e32 v130, v130, v200
	v_mul_f32_e32 v131, v131, v200
	v_mul_f32_e32 v132, v132, v200
	v_mul_f32_e32 v133, v133, v200
	v_mul_f32_e32 v134, v134, v200
	v_mul_f32_e32 v135, v135, v200
	v_mul_f32_e32 v136, v136, v201
	v_mul_f32_e32 v137, v137, v201
	v_mul_f32_e32 v138, v138, v201
	v_mul_f32_e32 v139, v139, v201
	v_mul_f32_e32 v140, v140, v201
	v_mul_f32_e32 v141, v141, v201
	v_mul_f32_e32 v142, v142, v201
	v_mul_f32_e32 v143, v143, v201
	v_mul_f32_e32 v144, v144, v202
	v_mul_f32_e32 v145, v145, v202
	v_mul_f32_e32 v146, v146, v202
	v_mul_f32_e32 v147, v147, v202
	v_mul_f32_e32 v148, v148, v202
	v_mul_f32_e32 v149, v149, v202
	v_mul_f32_e32 v150, v150, v202
	v_mul_f32_e32 v151, v151, v202
	v_mul_f32_e32 v152, v152, v203
	v_mul_f32_e32 v153, v153, v203
	v_mul_f32_e32 v154, v154, v203
	v_mul_f32_e32 v155, v155, v203
	v_mul_f32_e32 v156, v156, v203
	v_mul_f32_e32 v157, v157, v203
	v_mul_f32_e32 v158, v158, v203
	v_mul_f32_e32 v159, v159, v203
	v_cvt_pk_bf16_f32 v204, v128, v129
	v_cvt_pk_bf16_f32 v205, v130, v131
	v_cvt_pk_bf16_f32 v206, v132, v133
	v_cvt_pk_bf16_f32 v207, v134, v135
	v_cvt_pk_bf16_f32 v208, v136, v137
	v_cvt_pk_bf16_f32 v209, v138, v139
	v_cvt_pk_bf16_f32 v210, v140, v141
	v_cvt_pk_bf16_f32 v211, v142, v143
	v_cvt_pk_bf16_f32 v212, v144, v145
	v_cvt_pk_bf16_f32 v213, v146, v147
	v_cvt_pk_bf16_f32 v214, v148, v149
	v_cvt_pk_bf16_f32 v215, v150, v151
	v_cvt_pk_bf16_f32 v216, v152, v153
	v_cvt_pk_bf16_f32 v217, v154, v155
	v_cvt_pk_bf16_f32 v218, v156, v157
	v_cvt_pk_bf16_f32 v219, v158, v159
	global_store_dwordx4 v222, v[204:207], s[16:17] nt
	global_store_dwordx4 v222, v[208:211], s[16:17] offset:1024 nt
	global_store_dwordx4 v222, v[212:215], s[16:17] offset:2048 nt
	global_store_dwordx4 v222, v[216:219], s[16:17] offset:3072 nt
	s_cmpk_lt_i32 s21, 0x4000
	s_cbranch_scc0 .Lgate1_done
	s_mov_b32 s20, s21
	s_mov_b64 s[16:17], s[14:15]
	s_branch .Lgate1_topA
.Lgate1_done:
.LBB0_407:
	s_waitcnt vmcnt(0)
	s_and_b64 vcc, exec, s[70:71]
	s_barrier
	s_cbranch_vccnz .LBB0_415
	v_mbcnt_lo_u32_b32 v0, -1, 0
	v_mbcnt_hi_u32_b32 v0, -1, v0
	s_nop 0
	v_cmp_eq_u32_e32 vcc, 0, v0
	s_and_saveexec_b64 s[6:7], vcc
	s_cbranch_execz .LBB0_414
	s_mov_b64 s[10:11], exec
	buffer_wbl2 sc1
	s_waitcnt vmcnt(0)
	s_waitcnt vmcnt(0)
	v_mbcnt_lo_u32_b32 v0, s10, 0
	v_mbcnt_hi_u32_b32 v0, s11, v0
	v_cmp_eq_u32_e32 vcc, 0, v0
	s_and_saveexec_b64 s[12:13], vcc
	s_cbranch_execz .LBB0_411
	s_bcnt1_i32_b64 s0, s[10:11]
	v_mov_b32_e32 v0, 0
	v_mov_b32_e32 v1, s0
	global_atomic_add v0, v1, s[92:93]
